# accumulator zeroing by zero-operand MFMAs instead of 127 v_mov per unit
# speedup vs baseline: 1.0106x; 1.0106x over previous
.LBB0_109:
	s_ashr_i32 s89, s88, 31
	s_lshl_b64 s[8:9], s[88:89], 19
	s_add_u32 s90, s30, s8
	s_addc_u32 s91, s31, s9
	s_and_b64 s[8:9], s[0:1], exec
	s_cselect_b32 s7, s91, s39
	s_cselect_b32 s16, s90, s38
	s_ashr_i32 s87, s86, 31
	s_lshl_b64 s[8:9], s[86:87], 19
	s_add_u32 s92, s3, s8
	s_addc_u32 s93, s44, s9
	s_and_b64 s[8:9], s[0:1], exec
	s_cselect_b32 s17, s93, s37
	s_cselect_b32 s18, s92, s36
	s_add_u32 s94, s38, 0x40080
	s_addc_u32 s95, s39, 0
	s_add_u32 s28, s36, 0x100
	v_mov_b32_e32 v0, 0
	s_addc_u32 s29, s37, 0
	s_mov_b32 s42, -2
	v_mov_b32_e32 v156, 0
	v_mov_b32_e32 v157, 0
	v_mov_b32_e32 v158, 0
	v_mov_b32_e32 v159, 0
	s_nop 1
	v_mfma_f32_32x32x16_bf16 v[0:15], v[156:159], v[156:159], 0
	v_mfma_f32_32x32x16_bf16 v[16:31], v[156:159], v[156:159], 0
	v_mfma_f32_32x32x16_bf16 v[32:47], v[156:159], v[156:159], 0
	v_mfma_f32_32x32x16_bf16 v[48:63], v[156:159], v[156:159], 0
	v_mfma_f32_32x32x16_bf16 v[64:79], v[156:159], v[156:159], 0
	v_mfma_f32_32x32x16_bf16 v[80:95], v[156:159], v[156:159], 0
	v_mfma_f32_32x32x16_bf16 v[96:111], v[156:159], v[156:159], 0
	v_mfma_f32_32x32x16_bf16 v[112:127], v[156:159], v[156:159], 0

.LBB0_457:
	s_ashr_i32 s57, s56, 31
	s_lshl_b64 s[8:9], s[56:57], 19
	s_add_u32 s1, s30, s8
	s_addc_u32 s16, s31, s9
	s_ashr_i32 s8, s46, 1
	s_ashr_i32 s9, s8, 31
	s_lshl_b64 s[8:9], s[8:9], 9
	s_add_u32 s72, s1, s8
	s_addc_u32 s73, s16, s9
	s_and_b64 s[8:9], s[44:45], exec
	s_cselect_b32 s1, s73, s83
	s_cselect_b32 s16, s72, s82
	s_ashr_i32 s47, s46, 31
	s_lshl_b64 s[8:9], s[46:47], 17
	s_add_u32 s74, s3, s8
	s_addc_u32 s75, s27, s9
	s_and_b64 s[8:9], s[44:45], exec
	v_mov_b32_e32 v0, 0
	s_cselect_b32 s17, s75, s81
	s_cselect_b32 s28, s74, s80
	s_mov_b32 s18, 0
	s_mov_b64 s[84:85], -1
	s_mov_b64 s[36:37], 0
	v_mov_b32_e32 v28, 0
	v_mov_b32_e32 v29, 0
	v_mov_b32_e32 v30, 0
	v_mov_b32_e32 v31, 0
	s_nop 1
	v_mfma_f32_16x16x32_bf16 v[0:3], v[28:31], v[28:31], 0
	v_mfma_f32_16x16x32_bf16 v[4:7], v[28:31], v[28:31], 0
	v_mfma_f32_16x16x32_bf16 v[8:11], v[28:31], v[28:31], 0
	v_mfma_f32_16x16x32_bf16 v[12:15], v[28:31], v[28:31], 0
	v_mfma_f32_16x16x32_bf16 v[16:19], v[28:31], v[28:31], 0
	v_mfma_f32_16x16x32_bf16 v[20:23], v[28:31], v[28:31], 0
	v_mfma_f32_16x16x32_bf16 v[24:27], v[28:31], v[28:31], 0
	v_mfma_f32_16x16x32_bf16 v[36:39], v[28:31], v[28:31], 0
	v_mfma_f32_16x16x32_bf16 v[48:51], v[28:31], v[28:31], 0
	v_mfma_f32_16x16x32_bf16 v[52:55], v[28:31], v[28:31], 0
	v_mfma_f32_16x16x32_bf16 v[56:59], v[28:31], v[28:31], 0
	v_mfma_f32_16x16x32_bf16 v[60:63], v[28:31], v[28:31], 0
	v_mfma_f32_16x16x32_bf16 v[64:67], v[28:31], v[28:31], 0
	v_mfma_f32_16x16x32_bf16 v[68:71], v[28:31], v[28:31], 0
	v_mfma_f32_16x16x32_bf16 v[72:75], v[28:31], v[28:31], 0
	v_mfma_f32_16x16x32_bf16 v[76:79], v[28:31], v[28:31], 0
	v_mfma_f32_16x16x32_bf16 v[80:83], v[28:31], v[28:31], 0
	v_mfma_f32_16x16x32_bf16 v[84:87], v[28:31], v[28:31], 0
	v_mfma_f32_16x16x32_bf16 v[88:91], v[28:31], v[28:31], 0
	v_mfma_f32_16x16x32_bf16 v[92:95], v[28:31], v[28:31], 0
	v_mfma_f32_16x16x32_bf16 v[96:99], v[28:31], v[28:31], 0
	v_mfma_f32_16x16x32_bf16 v[100:103], v[28:31], v[28:31], 0
	v_mfma_f32_16x16x32_bf16 v[104:107], v[28:31], v[28:31], 0
	v_mfma_f32_16x16x32_bf16 v[108:111], v[28:31], v[28:31], 0
	v_mfma_f32_16x16x32_bf16 v[112:115], v[28:31], v[28:31], 0
	v_mfma_f32_16x16x32_bf16 v[116:119], v[28:31], v[28:31], 0
	v_mfma_f32_16x16x32_bf16 v[120:123], v[28:31], v[28:31], 0
	v_mfma_f32_16x16x32_bf16 v[124:127], v[28:31], v[28:31], 0
	v_mfma_f32_16x16x32_bf16 v[128:131], v[28:31], v[28:31], 0
	v_mfma_f32_16x16x32_bf16 v[132:135], v[28:31], v[28:31], 0
	v_mfma_f32_16x16x32_bf16 v[136:139], v[28:31], v[28:31], 0
	v_mfma_f32_16x16x32_bf16 v[140:143], v[28:31], v[28:31], 0

.LBB0_608:
	s_ashr_i32 s73, s72, 31
	s_lshl_b64 s[6:7], s[72:73], 19
	s_add_u32 s74, s30, s6
	s_addc_u32 s75, s31, s7
	s_and_b64 s[6:7], s[8:9], exec
	s_cselect_b32 s15, s75, s81
	s_cselect_b32 s42, s74, s80
	s_ashr_i32 s71, s70, 31
	s_lshl_b64 s[6:7], s[70:71], 19
	s_add_u32 s78, s94, s6
	s_addc_u32 s79, s95, s7
	s_and_b64 s[6:7], s[8:9], exec
	s_cselect_b32 s43, s79, s83
	s_cselect_b32 s69, s78, s82
	s_add_u32 s71, s80, 0x40000
	s_addc_u32 s73, s81, 0
	s_lshl_b32 s6, s72, 6
	s_ashr_i32 s7, s6, 31
	s_cmpk_lt_i32 s72, 0x42
	s_cselect_b32 s77, 16, 8
	s_lshl_b64 s[6:7], s[6:7], 2
	s_add_u32 s84, s3, s6
	v_mov_b32_e32 v0, 0
	s_addc_u32 s85, s27, s7
	s_mov_b32 s86, 0
	s_waitcnt lgkmcnt(0)
	v_mov_b32_e32 v142, 0
	v_mov_b32_e32 v143, 0
	v_mov_b32_e32 v144, 0
	v_mov_b32_e32 v145, 0
	s_nop 1
	v_mfma_f32_32x32x16_bf16 v[0:15], v[142:145], v[142:145], 0
	v_mfma_f32_32x32x16_bf16 v[16:31], v[142:145], v[142:145], 0
	v_mfma_f32_32x32x16_bf16 v[32:47], v[142:145], v[142:145], 0
	v_mfma_f32_32x32x16_bf16 v[48:63], v[142:145], v[142:145], 0
	v_mfma_f32_32x32x16_bf16 v[64:79], v[142:145], v[142:145], 0
	v_mfma_f32_32x32x16_bf16 v[80:95], v[142:145], v[142:145], 0
	v_mfma_f32_32x32x16_bf16 v[96:111], v[142:145], v[142:145], 0
	v_mfma_f32_32x32x16_bf16 v[112:127], v[142:145], v[142:145], 0
	s_branch .LBB0_612

.LBB0_687:
	v_mov_b32_e32 v127, 0
	s_and_b64 vcc, exec, s[0:1]
	v_mov_b32_e32 v142, 0
	v_mov_b32_e32 v143, 0
	v_mov_b32_e32 v144, 0
	v_mov_b32_e32 v145, 0
	s_nop 1
	v_mfma_f32_32x32x16_bf16 v[0:15], v[142:145], v[142:145], 0
	v_mfma_f32_32x32x16_bf16 v[16:31], v[142:145], v[142:145], 0
	v_mfma_f32_32x32x16_bf16 v[32:47], v[142:145], v[142:145], 0
	v_mfma_f32_32x32x16_bf16 v[48:63], v[142:145], v[142:145], 0
	v_mfma_f32_32x32x16_bf16 v[64:79], v[142:145], v[142:145], 0
	v_mfma_f32_32x32x16_bf16 v[80:95], v[142:145], v[142:145], 0
	v_mfma_f32_32x32x16_bf16 v[96:111], v[142:145], v[142:145], 0
	v_mfma_f32_32x32x16_bf16 v[112:127], v[142:145], v[142:145], 0
	s_cbranch_vccnz .LBB0_710
	s_add_u32 s42, s80, 0x40000
	s_addc_u32 s43, s81, 0
	s_lshl_b32 s6, s72, 6
	s_ashr_i32 s7, s6, 31
	s_cmpk_lt_i32 s72, 0x42
	s_cselect_b32 s51, 16, 8
	s_lshl_b64 s[6:7], s[6:7], 2
	s_add_u32 s86, s3, s6
	v_mov_b32_e32 v0, 0
	s_addc_u32 s87, s27, s7
	s_mov_b32 s88, 0
	v_mov_b32_e32 v142, 0
	v_mov_b32_e32 v143, 0
	v_mov_b32_e32 v144, 0
	v_mov_b32_e32 v145, 0
	s_nop 1
	v_mfma_f32_32x32x16_bf16 v[0:15], v[142:145], v[142:145], 0
	v_mfma_f32_32x32x16_bf16 v[16:31], v[142:145], v[142:145], 0
	v_mfma_f32_32x32x16_bf16 v[32:47], v[142:145], v[142:145], 0
	v_mfma_f32_32x32x16_bf16 v[48:63], v[142:145], v[142:145], 0
	v_mfma_f32_32x32x16_bf16 v[64:79], v[142:145], v[142:145], 0
	v_mfma_f32_32x32x16_bf16 v[80:95], v[142:145], v[142:145], 0
	v_mfma_f32_32x32x16_bf16 v[96:111], v[142:145], v[142:145], 0
	v_mfma_f32_32x32x16_bf16 v[112:127], v[142:145], v[142:145], 0
	s_branch .LBB0_692

.LBB0_1113:
	s_ashr_i32 s71, s70, 31
	s_lshl_b64 s[6:7], s[70:71], 19
	s_add_u32 s72, s30, s6
	s_addc_u32 s73, s31, s7
	s_and_b64 s[6:7], s[12:13], exec
	s_cselect_b32 s16, s73, s81
	s_cselect_b32 s17, s72, s80
	s_ashr_i32 s69, s68, 31
	s_lshl_b64 s[6:7], s[68:69], 19
	v_readlane_b32 s8, v254, 44
	s_add_u32 s74, s8, s6
	v_readlane_b32 s6, v254, 46
	s_addc_u32 s75, s6, s7
	s_and_b64 s[6:7], s[12:13], exec
	s_cselect_b32 s55, s75, s83
	s_cselect_b32 s63, s74, s82
	s_add_u32 s69, s80, 0x40000
	s_addc_u32 s71, s81, 0
	s_lshl_b32 s6, s70, 6
	s_ashr_i32 s7, s6, 31
	s_cmpk_lt_i32 s70, 0x42
	s_cselect_b32 s42, 8, 4
	s_lshl_b64 s[6:7], s[6:7], 2
	v_readlane_b32 s8, v255, 2
	s_add_u32 s84, s8, s6
	v_readlane_b32 s6, v255, 3
	v_mov_b32_e32 v0, 0
	s_addc_u32 s85, s6, s7
	s_mov_b32 s43, 0
	v_mov_b32_e32 v156, 0
	v_mov_b32_e32 v157, 0
	v_mov_b32_e32 v158, 0
	v_mov_b32_e32 v159, 0
	s_nop 1
	v_mfma_f32_32x32x16_bf16 v[0:15], v[156:159], v[156:159], 0
	v_mfma_f32_32x32x16_bf16 v[16:31], v[156:159], v[156:159], 0
	v_mfma_f32_32x32x16_bf16 v[32:47], v[156:159], v[156:159], 0
	v_mfma_f32_32x32x16_bf16 v[48:63], v[156:159], v[156:159], 0
	v_mfma_f32_32x32x16_bf16 v[64:79], v[156:159], v[156:159], 0
	v_mfma_f32_32x32x16_bf16 v[80:95], v[156:159], v[156:159], 0
	v_mfma_f32_32x32x16_bf16 v[96:111], v[156:159], v[156:159], 0
	v_mfma_f32_32x32x16_bf16 v[112:127], v[156:159], v[156:159], 0
	s_branch .LBB0_1117

.LBB0_1235:
	s_add_u32 s11, s78, 0xb0000
	s_addc_u32 s42, s79, 0
	s_lshl_b32 s6, s50, 6
	s_ashr_i32 s7, s6, 31
	s_lshl_b64 s[6:7], s[6:7], 2
	v_readlane_b32 s8, v254, 20
	s_add_u32 s82, s8, s6
	v_readlane_b32 s6, v254, 2
	v_mov_b32_e32 v0, 0
	s_addc_u32 s83, s6, s7
	s_mov_b32 s43, 0
	s_waitcnt lgkmcnt(0)
	v_mov_b32_e32 v142, 0
	v_mov_b32_e32 v143, 0
	v_mov_b32_e32 v144, 0
	v_mov_b32_e32 v145, 0
	s_nop 1
	v_mfma_f32_32x32x16_bf16 v[0:15], v[142:145], v[142:145], 0
	v_mfma_f32_32x32x16_bf16 v[16:31], v[142:145], v[142:145], 0
	v_mfma_f32_32x32x16_bf16 v[32:47], v[142:145], v[142:145], 0
	v_mfma_f32_32x32x16_bf16 v[48:63], v[142:145], v[142:145], 0
	v_mfma_f32_32x32x16_bf16 v[64:79], v[142:145], v[142:145], 0
	v_mfma_f32_32x32x16_bf16 v[80:95], v[142:145], v[142:145], 0
	v_mfma_f32_32x32x16_bf16 v[96:111], v[142:145], v[142:145], 0
	v_mfma_f32_32x32x16_bf16 v[112:127], v[142:145], v[142:145], 0
	s_branch .LBB0_1239

.LBB0_1316:
	v_mov_b32_e32 v123, 0
	s_andn2_b64 vcc, exec, s[62:63]
	v_mov_b32_e32 v142, 0
	v_mov_b32_e32 v143, 0
	v_mov_b32_e32 v144, 0
	v_mov_b32_e32 v145, 0
	s_nop 1
	v_mfma_f32_32x32x16_bf16 v[0:15], v[142:145], v[142:145], 0
	v_mfma_f32_32x32x16_bf16 v[16:31], v[142:145], v[142:145], 0
	v_mfma_f32_32x32x16_bf16 v[32:47], v[142:145], v[142:145], 0
	v_mfma_f32_32x32x16_bf16 v[48:63], v[142:145], v[142:145], 0
	v_mfma_f32_32x32x16_bf16 v[64:79], v[142:145], v[142:145], 0
	v_mfma_f32_32x32x16_bf16 v[80:95], v[142:145], v[142:145], 0
	v_mfma_f32_32x32x16_bf16 v[96:111], v[142:145], v[142:145], 0
	v_mfma_f32_32x32x16_bf16 v[112:127], v[142:145], v[142:145], 0
	s_cbranch_vccnz .LBB0_1339
	s_add_u32 s11, s78, 0xb0000
	s_addc_u32 s42, s79, 0
	s_lshl_b32 s6, s41, 6
	s_ashr_i32 s7, s6, 31
	s_lshl_b64 s[6:7], s[6:7], 2
	v_readlane_b32 s8, v254, 20
	s_add_u32 s84, s8, s6
	v_readlane_b32 s6, v254, 2
	v_mov_b32_e32 v0, 0
	s_addc_u32 s85, s6, s7
	s_mov_b32 s86, 0
	v_mov_b32_e32 v142, 0
	v_mov_b32_e32 v143, 0
	v_mov_b32_e32 v144, 0
	v_mov_b32_e32 v145, 0
	s_nop 1
	v_mfma_f32_32x32x16_bf16 v[0:15], v[142:145], v[142:145], 0
	v_mfma_f32_32x32x16_bf16 v[16:31], v[142:145], v[142:145], 0
	v_mfma_f32_32x32x16_bf16 v[32:47], v[142:145], v[142:145], 0
	v_mfma_f32_32x32x16_bf16 v[48:63], v[142:145], v[142:145], 0
	v_mfma_f32_32x32x16_bf16 v[64:79], v[142:145], v[142:145], 0
	v_mfma_f32_32x32x16_bf16 v[80:95], v[142:145], v[142:145], 0
	v_mfma_f32_32x32x16_bf16 v[96:111], v[142:145], v[142:145], 0
	v_mfma_f32_32x32x16_bf16 v[112:127], v[142:145], v[142:145], 0
	s_branch .LBB0_1321

.LBB0_1545:
	s_ashr_i32 s73, s72, 31
	s_lshl_b64 s[6:7], s[72:73], 19
	s_add_u32 s74, s30, s6
	s_addc_u32 s75, s31, s7
	s_and_b64 s[6:7], s[0:1], exec
	s_cselect_b32 s73, s75, s81
	s_cselect_b32 s3, s74, s80
	s_ashr_i32 s71, s70, 31
	s_lshl_b64 s[6:7], s[70:71], 19
	v_readlane_b32 s8, v254, 49
	v_readlane_b32 s9, v254, 50
	s_add_u32 s78, s8, s6
	s_addc_u32 s79, s9, s7
	s_and_b64 s[6:7], s[0:1], exec
	s_cselect_b32 s71, s79, s83
	s_cselect_b32 s33, s78, s82
	s_add_u32 s62, s80, 0x40000
	s_addc_u32 s63, s81, 0
	s_lshl_b32 s6, s72, 6
	s_ashr_i32 s7, s6, 31
	s_cmpk_lt_i32 s72, 0x42
	s_cselect_b32 s42, 8, 4
	s_lshl_b64 s[6:7], s[6:7], 2
	v_readlane_b32 s8, v255, 2
	s_add_u32 s84, s8, s6
	v_readlane_b32 s6, v255, 3
	v_mov_b32_e32 v0, 0
	s_addc_u32 s85, s6, s7
	s_mov_b32 s43, 0
	v_mov_b32_e32 v144, 0
	v_mov_b32_e32 v145, 0
	v_mov_b32_e32 v146, 0
	v_mov_b32_e32 v147, 0
	s_nop 1
	v_mfma_f32_32x32x16_bf16 v[0:15], v[144:147], v[144:147], 0
	v_mfma_f32_32x32x16_bf16 v[16:31], v[144:147], v[144:147], 0
	v_mfma_f32_32x32x16_bf16 v[32:47], v[144:147], v[144:147], 0
	v_mfma_f32_32x32x16_bf16 v[48:63], v[144:147], v[144:147], 0
	v_mfma_f32_32x32x16_bf16 v[64:79], v[144:147], v[144:147], 0
	v_mfma_f32_32x32x16_bf16 v[80:95], v[144:147], v[144:147], 0
	v_mfma_f32_32x32x16_bf16 v[96:111], v[144:147], v[144:147], 0
	v_mfma_f32_32x32x16_bf16 v[112:127], v[144:147], v[144:147], 0
	s_branch .LBB0_1549

.LBB0_1852:
	s_ashr_i32 s71, s70, 31
	s_lshl_b64 s[6:7], s[70:71], 19
	s_add_u32 s72, s30, s6
	s_addc_u32 s73, s31, s7
	s_and_b64 s[6:7], s[14:15], exec
	s_cselect_b32 s40, s73, s77
	s_cselect_b32 s41, s72, s76
	s_ashr_i32 s69, s68, 31
	s_lshl_b64 s[6:7], s[68:69], 19
	v_readlane_b32 s8, v254, 47
	v_readlane_b32 s9, v254, 48
	s_add_u32 s74, s8, s6
	s_addc_u32 s75, s9, s7
	s_and_b64 s[6:7], s[14:15], exec
	s_cselect_b32 s42, s75, s79
	s_cselect_b32 s43, s74, s78
	s_add_u32 s48, s76, 0x40000
	s_addc_u32 s49, s77, 0
	s_lshl_b32 s6, s70, 6
	s_ashr_i32 s7, s6, 31
	s_cmpk_lt_i32 s70, 0x42
	s_cselect_b32 s53, 8, 4
	s_lshl_b64 s[6:7], s[6:7], 2
	s_add_u32 s80, s3, s6
	v_mov_b32_e32 v0, 0
	s_addc_u32 s81, s33, s7
	s_mov_b32 s55, 0
	s_waitcnt lgkmcnt(0)
	v_mov_b32_e32 v142, 0
	v_mov_b32_e32 v143, 0
	v_mov_b32_e32 v144, 0
	v_mov_b32_e32 v145, 0
	s_nop 1
	v_mfma_f32_32x32x16_bf16 v[0:15], v[142:145], v[142:145], 0
	v_mfma_f32_32x32x16_bf16 v[16:31], v[142:145], v[142:145], 0
	v_mfma_f32_32x32x16_bf16 v[32:47], v[142:145], v[142:145], 0
	v_mfma_f32_32x32x16_bf16 v[48:63], v[142:145], v[142:145], 0
	v_mfma_f32_32x32x16_bf16 v[64:79], v[142:145], v[142:145], 0
	v_mfma_f32_32x32x16_bf16 v[80:95], v[142:145], v[142:145], 0
	v_mfma_f32_32x32x16_bf16 v[96:111], v[142:145], v[142:145], 0
	v_mfma_f32_32x32x16_bf16 v[112:127], v[142:145], v[142:145], 0
	s_branch .LBB0_1856

.LBB0_1931:
	v_mov_b32_e32 v127, 0
	s_and_b64 vcc, exec, s[0:1]
	v_mov_b32_e32 v142, 0
	v_mov_b32_e32 v143, 0
	v_mov_b32_e32 v144, 0
	v_mov_b32_e32 v145, 0
	s_nop 1
	v_mfma_f32_32x32x16_bf16 v[0:15], v[142:145], v[142:145], 0
	v_mfma_f32_32x32x16_bf16 v[16:31], v[142:145], v[142:145], 0
	v_mfma_f32_32x32x16_bf16 v[32:47], v[142:145], v[142:145], 0
	v_mfma_f32_32x32x16_bf16 v[48:63], v[142:145], v[142:145], 0
	v_mfma_f32_32x32x16_bf16 v[64:79], v[142:145], v[142:145], 0
	v_mfma_f32_32x32x16_bf16 v[80:95], v[142:145], v[142:145], 0
	v_mfma_f32_32x32x16_bf16 v[96:111], v[142:145], v[142:145], 0
	v_mfma_f32_32x32x16_bf16 v[112:127], v[142:145], v[142:145], 0
	s_cbranch_vccnz .LBB0_1954
	s_add_u32 s42, s70, 0x40000
	s_addc_u32 s43, s71, 0
	s_lshl_b32 s6, s62, 6
	s_ashr_i32 s7, s6, 31
	s_cmpk_lt_i32 s62, 0x42
	s_cselect_b32 s49, 8, 4
	s_lshl_b64 s[6:7], s[6:7], 2
	s_add_u32 s76, s3, s6
	v_mov_b32_e32 v0, 0
	s_addc_u32 s77, s33, s7
	s_mov_b32 s78, 0
	v_mov_b32_e32 v142, 0
	v_mov_b32_e32 v143, 0
	v_mov_b32_e32 v144, 0
	v_mov_b32_e32 v145, 0
	s_nop 1
	v_mfma_f32_32x32x16_bf16 v[0:15], v[142:145], v[142:145], 0
	v_mfma_f32_32x32x16_bf16 v[16:31], v[142:145], v[142:145], 0
	v_mfma_f32_32x32x16_bf16 v[32:47], v[142:145], v[142:145], 0
	v_mfma_f32_32x32x16_bf16 v[48:63], v[142:145], v[142:145], 0
	v_mfma_f32_32x32x16_bf16 v[64:79], v[142:145], v[142:145], 0
	v_mfma_f32_32x32x16_bf16 v[80:95], v[142:145], v[142:145], 0
	v_mfma_f32_32x32x16_bf16 v[96:111], v[142:145], v[142:145], 0
	v_mfma_f32_32x32x16_bf16 v[112:127], v[142:145], v[142:145], 0
	s_branch .LBB0_1936

.LBB0_2158:
	s_ashr_i32 s57, s56, 31
	s_lshl_b64 s[6:7], s[56:57], 19
	s_add_u32 s58, s30, s6
	s_addc_u32 s59, s31, s7
	s_and_b64 s[6:7], s[8:9], exec
	s_cselect_b32 s1, s59, s63
	s_cselect_b32 s15, s58, s62
	s_ashr_i32 s55, s54, 31
	s_lshl_b64 s[6:7], s[54:55], 19
	s_add_u32 s60, s27, s6
	s_addc_u32 s61, s28, s7
	s_and_b64 s[6:7], s[8:9], exec
	s_cselect_b32 s53, s61, s65
	s_cselect_b32 s55, s60, s64
	s_add_u32 s57, s62, 0x40000
	s_addc_u32 s33, s63, 0
	s_lshl_b32 s6, s56, 6
	s_ashr_i32 s7, s6, 31
	s_cmpk_lt_i32 s56, 0x42
	s_cselect_b32 s42, 8, 4
	s_lshl_b64 s[6:7], s[6:7], 2
	v_readlane_b32 s10, v254, 47
	s_add_u32 s66, s10, s6
	v_readlane_b32 s6, v255, 2
	v_mov_b32_e32 v0, 0
	s_addc_u32 s67, s6, s7
	s_mov_b32 s43, 0
	v_mov_b32_e32 v156, 0
	v_mov_b32_e32 v157, 0
	v_mov_b32_e32 v158, 0
	v_mov_b32_e32 v159, 0
	s_nop 1
	v_mfma_f32_32x32x16_bf16 v[0:15], v[156:159], v[156:159], 0
	v_mfma_f32_32x32x16_bf16 v[16:31], v[156:159], v[156:159], 0
	v_mfma_f32_32x32x16_bf16 v[32:47], v[156:159], v[156:159], 0
	v_mfma_f32_32x32x16_bf16 v[48:63], v[156:159], v[156:159], 0
	v_mfma_f32_32x32x16_bf16 v[64:79], v[156:159], v[156:159], 0
	v_mfma_f32_32x32x16_bf16 v[80:95], v[156:159], v[156:159], 0
	v_mfma_f32_32x32x16_bf16 v[96:111], v[156:159], v[156:159], 0
	v_mfma_f32_32x32x16_bf16 v[112:127], v[156:159], v[156:159], 0
	s_branch .LBB0_2162

.LBB0_2280:
	s_add_u32 s41, s60, 0xb0000
	s_addc_u32 s42, s61, 0
	s_lshl_b32 s18, s75, 6
	s_ashr_i32 s19, s18, 31
	s_lshl_b64 s[18:19], s[18:19], 2
	v_readlane_b32 s14, v254, 20
	s_add_u32 s64, s14, s18
	v_readlane_b32 s14, v254, 2
	v_mov_b32_e32 v0, 0
	s_addc_u32 s65, s14, s19
	s_mov_b32 s43, 0
	s_waitcnt lgkmcnt(0)
	v_mov_b32_e32 v142, 0
	v_mov_b32_e32 v143, 0
	v_mov_b32_e32 v144, 0
	v_mov_b32_e32 v145, 0
	s_nop 1
	v_mfma_f32_32x32x16_bf16 v[0:15], v[142:145], v[142:145], 0
	v_mfma_f32_32x32x16_bf16 v[16:31], v[142:145], v[142:145], 0
	v_mfma_f32_32x32x16_bf16 v[32:47], v[142:145], v[142:145], 0
	v_mfma_f32_32x32x16_bf16 v[48:63], v[142:145], v[142:145], 0
	v_mfma_f32_32x32x16_bf16 v[64:79], v[142:145], v[142:145], 0
	v_mfma_f32_32x32x16_bf16 v[80:95], v[142:145], v[142:145], 0
	v_mfma_f32_32x32x16_bf16 v[96:111], v[142:145], v[142:145], 0
	v_mfma_f32_32x32x16_bf16 v[112:127], v[142:145], v[142:145], 0
	s_branch .LBB0_2284

.LBB0_2359:
	v_mov_b32_e32 v123, 0
	s_andn2_b64 vcc, exec, s[14:15]
	v_mov_b32_e32 v142, 0
	v_mov_b32_e32 v143, 0
	v_mov_b32_e32 v144, 0
	v_mov_b32_e32 v145, 0
	s_nop 1
	v_mfma_f32_32x32x16_bf16 v[0:15], v[142:145], v[142:145], 0
	v_mfma_f32_32x32x16_bf16 v[16:31], v[142:145], v[142:145], 0
	v_mfma_f32_32x32x16_bf16 v[32:47], v[142:145], v[142:145], 0
	v_mfma_f32_32x32x16_bf16 v[48:63], v[142:145], v[142:145], 0
	v_mfma_f32_32x32x16_bf16 v[64:79], v[142:145], v[142:145], 0
	v_mfma_f32_32x32x16_bf16 v[80:95], v[142:145], v[142:145], 0
	v_mfma_f32_32x32x16_bf16 v[96:111], v[142:145], v[142:145], 0
	v_mfma_f32_32x32x16_bf16 v[112:127], v[142:145], v[142:145], 0
	s_cbranch_vccnz .LBB0_2382
	s_add_u32 s35, s62, 0xb0000
	s_addc_u32 s42, s63, 0
	s_lshl_b32 s18, s84, 6
	s_ashr_i32 s19, s18, 31
	s_lshl_b64 s[18:19], s[18:19], 2
	v_readlane_b32 s6, v254, 20
	s_add_u32 s68, s6, s18
	v_readlane_b32 s6, v254, 2
	v_mov_b32_e32 v0, 0
	s_addc_u32 s69, s6, s19
	s_mov_b32 s70, 0
	v_mov_b32_e32 v142, 0
	v_mov_b32_e32 v143, 0
	v_mov_b32_e32 v144, 0
	v_mov_b32_e32 v145, 0
	s_nop 1
	v_mfma_f32_32x32x16_bf16 v[0:15], v[142:145], v[142:145], 0
	v_mfma_f32_32x32x16_bf16 v[16:31], v[142:145], v[142:145], 0
	v_mfma_f32_32x32x16_bf16 v[32:47], v[142:145], v[142:145], 0
	v_mfma_f32_32x32x16_bf16 v[48:63], v[142:145], v[142:145], 0
	v_mfma_f32_32x32x16_bf16 v[64:79], v[142:145], v[142:145], 0
	v_mfma_f32_32x32x16_bf16 v[80:95], v[142:145], v[142:145], 0
	v_mfma_f32_32x32x16_bf16 v[96:111], v[142:145], v[142:145], 0
	v_mfma_f32_32x32x16_bf16 v[112:127], v[142:145], v[142:145], 0
	s_branch .LBB0_2364
